# scan loop: DPP wait states filled with the next-step LDS prefetch reads instead of s_nop
# baseline (speedup 1.0000x reference)
; #define LAS __attribute__((address_space(3)))
; __device__ __forceinline__ float red4(float x) { x = DPP_ADD(x, 0xB1); x = DPP_ADD(x, 0x4E); return x; }
; __device__ __forceinline__ void phase_scan(const ScanArgs A, LAS unsigned char* lds) {
;     ...
;                 for (int t = 0; t < 16; ++t) {
;                     const LAS float* q = in + t * 64 + kq * 16;
;                     f32x4 Wv[4], KDv[4], Bv[4], ANv[4], Rv[4];
; #pragma unroll
;                     for (int j = 0; j < 4; ++j) { Wv[j] = *(const LAS f32x4*)(q + 4 * j); KDv[j] = *(const LAS f32x4*)(q + 1024 + 4 * j); Bv[j] = *(const LAS f32x4*)(q + 2048 + 4 * j);
;                                                   ANv[j] = *(const LAS f32x4*)(q + 3072 + 4 * j); Rv[j] = *(const LAS f32x4*)(q + 4096 + 4 * j); }
;                     const f32x2 v2 = *(const LAS f32x2*)(in + 5120 + t * 64 + half * 32 + rb * 2);
;     ...
;                     float sa[2], y[2];
; #pragma unroll
;                     for (int i = 0; i < 2; ++i) { f32x2 a0 = {0.f, 0.f}, a1 = {0.f, 0.f};
; #pragma unroll
;                         for (int p = 0; p < 8; p += 2) { a0 += S2[i][p] * PAIR(ANv, p); a1 += S2[i][p + 1] * PAIR(ANv, p + 1); }
;                         a0 += a1; sa[i] = red4(a0[0] + a0[1]); }
; #pragma unroll
;                     for (int i = 0; i < 2; ++i) { f32x2 y0 = {0.f, 0.f}, y1 = {0.f, 0.f}; const f32x2 sai = {sa[i], sa[i]}, vi = {v2[i], v2[i]};
; #pragma unroll
;                         for (int p = 0; p < 8; p += 2) {
;                             const f32x2 n0 = S2[i][p] * PAIR(Wv, p) + sai * PAIR(Bv, p) + vi * PAIR(KDv, p);
;                             const f32x2 n1 = S2[i][p + 1] * PAIR(Wv, p + 1) + sai * PAIR(Bv, p + 1) + vi * PAIR(KDv, p + 1);
;                             S2[i][p] = n0; S2[i][p + 1] = n1; y0 += n0 * PAIR(Rv, p); y1 += n1 * PAIR(Rv, p + 1); }
;                         y0 += y1; y[i] = red4(y0[0] + y0[1]); }
.Lscan_step:
	s_waitcnt lgkmcnt(15)
	v_pk_fma_f32 v[160:161], v[84:85], v[32:33], 0 op_sel_hi:[1,1,0]
	v_pk_fma_f32 v[162:163], v[88:89], v[34:35], 0 op_sel_hi:[1,1,0]
	v_pk_fma_f32 v[164:165], v[100:101], v[32:33], 0 op_sel_hi:[1,1,0]
	v_pk_fma_f32 v[166:167], v[104:105], v[34:35], 0 op_sel_hi:[1,1,0]
	v_pk_fma_f32 v[160:161], v[86:87], v[36:37], v[160:161]
	v_pk_fma_f32 v[162:163], v[92:93], v[38:39], v[162:163]
	v_pk_fma_f32 v[164:165], v[106:107], v[36:37], v[164:165]
	v_pk_fma_f32 v[166:167], v[108:109], v[38:39], v[166:167]
	v_pk_fma_f32 v[160:161], v[90:91], v[40:41], v[160:161]
	v_pk_fma_f32 v[162:163], v[98:99], v[42:43], v[162:163]
	v_pk_fma_f32 v[164:165], v[110:111], v[40:41], v[164:165]
	v_pk_fma_f32 v[166:167], v[112:113], v[42:43], v[166:167]
	v_pk_fma_f32 v[160:161], v[94:95], v[44:45], v[160:161]
	v_pk_fma_f32 v[162:163], v[102:103], v[46:47], v[162:163]
	v_pk_fma_f32 v[164:165], v[114:115], v[44:45], v[164:165]
	v_pk_fma_f32 v[166:167], v[116:117], v[46:47], v[166:167]
	v_pk_add_f32 v[160:161], v[162:163], v[160:161]
	v_pk_add_f32 v[164:165], v[166:167], v[164:165]
	ds_read_b128 v[32:35], v171 offset:12544
	v_add_f32_e32 v168, v160, v161
	v_add_f32_e32 v169, v164, v165
	ds_read_b128 v[36:39], v171 offset:12560
	v_add_f32_dpp v168, v168, v168 quad_perm:[1,0,3,2] row_mask:0xf bank_mask:0xf bound_ctrl:1
	v_add_f32_dpp v169, v169, v169 quad_perm:[1,0,3,2] row_mask:0xf bank_mask:0xf bound_ctrl:1
	ds_read_b128 v[40:43], v171 offset:12576
	v_add_f32_dpp v190, v168, v168 quad_perm:[2,3,0,1] row_mask:0xf bank_mask:0xf bound_ctrl:1
	v_add_f32_dpp v192, v169, v169 quad_perm:[2,3,0,1] row_mask:0xf bank_mask:0xf bound_ctrl:1
	ds_read_b128 v[44:47], v171 offset:12592
	s_waitcnt lgkmcnt(9)
	v_pk_mul_f32 v[216:217], v[142:143], v[190:191] op_sel_hi:[1,0]
	v_pk_mul_f32 v[218:219], v[144:145], v[190:191] op_sel_hi:[1,0]
	v_pk_mul_f32 v[232:233], v[142:143], v[192:193] op_sel_hi:[1,0]
	v_pk_mul_f32 v[234:235], v[144:145], v[192:193] op_sel_hi:[1,0]
	v_pk_fma_f32 v[216:217], v[84:85], v[48:49], v[216:217]
	v_pk_fma_f32 v[218:219], v[88:89], v[50:51], v[218:219]
	v_pk_fma_f32 v[232:233], v[100:101], v[48:49], v[232:233]
	v_pk_fma_f32 v[234:235], v[104:105], v[50:51], v[234:235]
	v_pk_fma_f32 v[84:85], v[172:173], v[188:189], v[216:217] op_sel_hi:[1,0,1]
	v_pk_fma_f32 v[88:89], v[174:175], v[188:189], v[218:219] op_sel_hi:[1,0,1]
	v_pk_fma_f32 v[100:101], v[172:173], v[188:189], v[232:233] op_sel:[0,1,0]
	v_pk_fma_f32 v[104:105], v[174:175], v[188:189], v[234:235] op_sel:[0,1,0]
	ds_read_b128 v[142:145], v171 offset:8448
	ds_read_b128 v[48:51], v171 offset:256
	ds_read_b128 v[172:175], v171 offset:4352
	v_pk_mul_f32 v[220:221], v[146:147], v[190:191] op_sel_hi:[1,0]
	v_pk_mul_f32 v[222:223], v[148:149], v[190:191] op_sel_hi:[1,0]
	v_pk_mul_f32 v[236:237], v[146:147], v[192:193] op_sel_hi:[1,0]
	v_pk_mul_f32 v[238:239], v[148:149], v[192:193] op_sel_hi:[1,0]
	v_pk_fma_f32 v[220:221], v[86:87], v[52:53], v[220:221]
	v_pk_fma_f32 v[222:223], v[92:93], v[54:55], v[222:223]
	v_pk_fma_f32 v[236:237], v[106:107], v[52:53], v[236:237]
	v_pk_fma_f32 v[238:239], v[108:109], v[54:55], v[238:239]
	v_pk_fma_f32 v[86:87], v[176:177], v[188:189], v[220:221] op_sel_hi:[1,0,1]
	v_pk_fma_f32 v[92:93], v[178:179], v[188:189], v[222:223] op_sel_hi:[1,0,1]
	v_pk_fma_f32 v[106:107], v[176:177], v[188:189], v[236:237] op_sel:[0,1,0]
	v_pk_fma_f32 v[108:109], v[178:179], v[188:189], v[238:239] op_sel:[0,1,0]
	ds_read_b128 v[146:149], v171 offset:8464
	ds_read_b128 v[52:55], v171 offset:272
	ds_read_b128 v[176:179], v171 offset:4368
	v_pk_mul_f32 v[224:225], v[150:151], v[190:191] op_sel_hi:[1,0]
	v_pk_mul_f32 v[226:227], v[152:153], v[190:191] op_sel_hi:[1,0]
	v_pk_mul_f32 v[240:241], v[150:151], v[192:193] op_sel_hi:[1,0]
	v_pk_mul_f32 v[242:243], v[152:153], v[192:193] op_sel_hi:[1,0]
	v_pk_fma_f32 v[224:225], v[90:91], v[56:57], v[224:225]
	v_pk_fma_f32 v[226:227], v[98:99], v[58:59], v[226:227]
	v_pk_fma_f32 v[240:241], v[110:111], v[56:57], v[240:241]
	v_pk_fma_f32 v[242:243], v[112:113], v[58:59], v[242:243]
	v_pk_fma_f32 v[90:91], v[180:181], v[188:189], v[224:225] op_sel_hi:[1,0,1]
	v_pk_fma_f32 v[98:99], v[182:183], v[188:189], v[226:227] op_sel_hi:[1,0,1]
	v_pk_fma_f32 v[110:111], v[180:181], v[188:189], v[240:241] op_sel:[0,1,0]
	v_pk_fma_f32 v[112:113], v[182:183], v[188:189], v[242:243] op_sel:[0,1,0]
	ds_read_b128 v[150:153], v171 offset:8480
	ds_read_b128 v[56:59], v171 offset:288
	ds_read_b128 v[180:183], v171 offset:4384
	v_pk_mul_f32 v[228:229], v[154:155], v[190:191] op_sel_hi:[1,0]
	v_pk_mul_f32 v[230:231], v[156:157], v[190:191] op_sel_hi:[1,0]
	v_pk_mul_f32 v[244:245], v[154:155], v[192:193] op_sel_hi:[1,0]
	v_pk_mul_f32 v[246:247], v[156:157], v[192:193] op_sel_hi:[1,0]
	v_pk_fma_f32 v[228:229], v[94:95], v[60:61], v[228:229]
	v_pk_fma_f32 v[230:231], v[102:103], v[62:63], v[230:231]
	v_pk_fma_f32 v[244:245], v[114:115], v[60:61], v[244:245]
	v_pk_fma_f32 v[246:247], v[116:117], v[62:63], v[246:247]
	v_pk_fma_f32 v[94:95], v[184:185], v[188:189], v[228:229] op_sel_hi:[1,0,1]
	v_pk_fma_f32 v[102:103], v[186:187], v[188:189], v[230:231] op_sel_hi:[1,0,1]
	v_pk_fma_f32 v[114:115], v[184:185], v[188:189], v[244:245] op_sel:[0,1,0]
	v_pk_fma_f32 v[116:117], v[186:187], v[188:189], v[246:247] op_sel:[0,1,0]
	ds_read_b128 v[154:157], v171 offset:8496
	ds_read_b128 v[60:63], v171 offset:304
	ds_read_b128 v[184:187], v171 offset:4400
	ds_read_b64 v[188:189], v96 offset:256
	s_waitcnt lgkmcnt(15)
; #define LAS __attribute__((address_space(3)))
; __device__ __forceinline__ float red4(float x) { x = DPP_ADD(x, 0xB1); x = DPP_ADD(x, 0x4E); return x; }
; __device__ __forceinline__ void phase_scan(const ScanArgs A, LAS unsigned char* lds) {
;     ...
;                 for (int t = 0; t < 16; ++t) {
;                     const LAS float* q = in + t * 64 + kq * 16;
;                     f32x4 Wv[4], KDv[4], Bv[4], ANv[4], Rv[4];
; #pragma unroll
;                     for (int j = 0; j < 4; ++j) { Wv[j] = *(const LAS f32x4*)(q + 4 * j); KDv[j] = *(const LAS f32x4*)(q + 1024 + 4 * j); Bv[j] = *(const LAS f32x4*)(q + 2048 + 4 * j);
;                                                   ANv[j] = *(const LAS f32x4*)(q + 3072 + 4 * j); Rv[j] = *(const LAS f32x4*)(q + 4096 + 4 * j); }
;                     const f32x2 v2 = *(const LAS f32x2*)(in + 5120 + t * 64 + half * 32 + rb * 2);
;     ...
;                     float sa[2], y[2];
; #pragma unroll
;                     for (int i = 0; i < 2; ++i) { f32x2 a0 = {0.f, 0.f}, a1 = {0.f, 0.f};
; #pragma unroll
;                         for (int p = 0; p < 8; p += 2) { a0 += S2[i][p] * PAIR(ANv, p); a1 += S2[i][p + 1] * PAIR(ANv, p + 1); }
;                         a0 += a1; sa[i] = red4(a0[0] + a0[1]); }
;     ...
;                     for (int i = 0; i < 2; ++i) { f32x2 y0 = {0.f, 0.f}, y1 = {0.f, 0.f}; const f32x2 sai = {sa[i], sa[i]}, vi = {v2[i], v2[i]};
; #pragma unroll
;                         for (int p = 0; p < 8; p += 2) {
;                             const f32x2 n0 = S2[i][p] * PAIR(Wv, p) + sai * PAIR(Bv, p) + vi * PAIR(KDv, p);
;                             const f32x2 n1 = S2[i][p + 1] * PAIR(Wv, p + 1) + sai * PAIR(Bv, p + 1) + vi * PAIR(KDv, p + 1);
;                             S2[i][p] = n0; S2[i][p + 1] = n1; y0 += n0 * PAIR(Rv, p); y1 += n1 * PAIR(Rv, p + 1); }
;                         y0 += y1; y[i] = red4(y0[0] + y0[1]); }
;     ...
;                     if (kq == 0) *(LAS f32x2*)(yb + t * 64 + half * 32 + rb * 2) = (f32x2){y[0], y[1]};
	v_pk_fma_f32 v[248:249], v[200:201], v[84:85], 0 op_sel_hi:[1,1,0]
	v_pk_fma_f32 v[250:251], v[202:203], v[88:89], 0 op_sel_hi:[1,1,0]
	v_pk_fma_f32 v[194:195], v[200:201], v[100:101], 0 op_sel_hi:[1,1,0]
	v_pk_fma_f32 v[158:159], v[202:203], v[104:105], 0 op_sel_hi:[1,1,0]
	v_pk_fma_f32 v[248:249], v[204:205], v[86:87], v[248:249]
	v_pk_fma_f32 v[250:251], v[206:207], v[92:93], v[250:251]
	v_pk_fma_f32 v[194:195], v[204:205], v[106:107], v[194:195]
	v_pk_fma_f32 v[158:159], v[206:207], v[108:109], v[158:159]
	v_pk_fma_f32 v[248:249], v[208:209], v[90:91], v[248:249]
	v_pk_fma_f32 v[250:251], v[210:211], v[98:99], v[250:251]
	v_pk_fma_f32 v[194:195], v[208:209], v[110:111], v[194:195]
	v_pk_fma_f32 v[158:159], v[210:211], v[112:113], v[158:159]
	v_pk_fma_f32 v[248:249], v[212:213], v[94:95], v[248:249]
	v_pk_fma_f32 v[250:251], v[214:215], v[102:103], v[250:251]
	v_pk_fma_f32 v[194:195], v[212:213], v[114:115], v[194:195]
	v_pk_fma_f32 v[158:159], v[214:215], v[116:117], v[158:159]
	v_pk_add_f32 v[248:249], v[250:251], v[248:249]
	v_pk_add_f32 v[194:195], v[158:159], v[194:195]
	ds_read_b128 v[200:203], v171 offset:16640
	v_add_f32_e32 v168, v248, v249
	v_add_f32_e32 v169, v194, v195
	ds_read_b128 v[204:207], v171 offset:16656
	v_add_f32_dpp v168, v168, v168 quad_perm:[1,0,3,2] row_mask:0xf bank_mask:0xf bound_ctrl:1
	v_add_f32_dpp v169, v169, v169 quad_perm:[1,0,3,2] row_mask:0xf bank_mask:0xf bound_ctrl:1
	ds_read_b128 v[208:211], v171 offset:16672
	v_add_f32_dpp v168, v168, v168 quad_perm:[2,3,0,1] row_mask:0xf bank_mask:0xf bound_ctrl:1
	v_add_f32_dpp v169, v169, v169 quad_perm:[2,3,0,1] row_mask:0xf bank_mask:0xf bound_ctrl:1
	ds_read_b128 v[212:215], v171 offset:16688
	s_and_saveexec_b64 s[34:35], s[8:9]
	ds_write_b64 v75, v[168:169] offset:0
	s_or_b64 exec, exec, s[34:35]
	s_waitcnt lgkmcnt(15)
	v_pk_fma_f32 v[160:161], v[84:85], v[32:33], 0 op_sel_hi:[1,1,0]
	v_pk_fma_f32 v[162:163], v[88:89], v[34:35], 0 op_sel_hi:[1,1,0]
	v_pk_fma_f32 v[164:165], v[100:101], v[32:33], 0 op_sel_hi:[1,1,0]
	v_pk_fma_f32 v[166:167], v[104:105], v[34:35], 0 op_sel_hi:[1,1,0]
	v_pk_fma_f32 v[160:161], v[86:87], v[36:37], v[160:161]
	v_pk_fma_f32 v[162:163], v[92:93], v[38:39], v[162:163]
	v_pk_fma_f32 v[164:165], v[106:107], v[36:37], v[164:165]
	v_pk_fma_f32 v[166:167], v[108:109], v[38:39], v[166:167]
	v_pk_fma_f32 v[160:161], v[90:91], v[40:41], v[160:161]
	v_pk_fma_f32 v[162:163], v[98:99], v[42:43], v[162:163]
	v_pk_fma_f32 v[164:165], v[110:111], v[40:41], v[164:165]
	v_pk_fma_f32 v[166:167], v[112:113], v[42:43], v[166:167]
	v_pk_fma_f32 v[160:161], v[94:95], v[44:45], v[160:161]
	v_pk_fma_f32 v[162:163], v[102:103], v[46:47], v[162:163]
	v_pk_fma_f32 v[164:165], v[114:115], v[44:45], v[164:165]
	v_pk_fma_f32 v[166:167], v[116:117], v[46:47], v[166:167]
	v_pk_add_f32 v[160:161], v[162:163], v[160:161]
	v_pk_add_f32 v[164:165], v[166:167], v[164:165]
	ds_read_b128 v[32:35], v171 offset:12800
	v_add_f32_e32 v168, v160, v161
	v_add_f32_e32 v169, v164, v165
	ds_read_b128 v[36:39], v171 offset:12816
	v_add_f32_dpp v168, v168, v168 quad_perm:[1,0,3,2] row_mask:0xf bank_mask:0xf bound_ctrl:1
	v_add_f32_dpp v169, v169, v169 quad_perm:[1,0,3,2] row_mask:0xf bank_mask:0xf bound_ctrl:1
	ds_read_b128 v[40:43], v171 offset:12832
	v_add_f32_dpp v190, v168, v168 quad_perm:[2,3,0,1] row_mask:0xf bank_mask:0xf bound_ctrl:1
	v_add_f32_dpp v192, v169, v169 quad_perm:[2,3,0,1] row_mask:0xf bank_mask:0xf bound_ctrl:1
	ds_read_b128 v[44:47], v171 offset:12848
	s_waitcnt lgkmcnt(9)
; #define LAS __attribute__((address_space(3)))
; __device__ __forceinline__ float red4(float x) { x = DPP_ADD(x, 0xB1); x = DPP_ADD(x, 0x4E); return x; }
; __device__ __forceinline__ void phase_scan(const ScanArgs A, LAS unsigned char* lds) {
;     ...
;                     for (int i = 0; i < 2; ++i) { f32x2 y0 = {0.f, 0.f}, y1 = {0.f, 0.f}; const f32x2 sai = {sa[i], sa[i]}, vi = {v2[i], v2[i]};
; #pragma unroll
;                         for (int p = 0; p < 8; p += 2) {
;                             const f32x2 n0 = S2[i][p] * PAIR(Wv, p) + sai * PAIR(Bv, p) + vi * PAIR(KDv, p);
;                             const f32x2 n1 = S2[i][p + 1] * PAIR(Wv, p + 1) + sai * PAIR(Bv, p + 1) + vi * PAIR(KDv, p + 1);
;                             S2[i][p] = n0; S2[i][p + 1] = n1; y0 += n0 * PAIR(Rv, p); y1 += n1 * PAIR(Rv, p + 1); }
;                         y0 += y1; y[i] = red4(y0[0] + y0[1]); }
;     ...
;                     if (kq == 0) *(LAS f32x2*)(yb + t * 64 + half * 32 + rb * 2) = (f32x2){y[0], y[1]};
	v_pk_mul_f32 v[216:217], v[142:143], v[190:191] op_sel_hi:[1,0]
	v_pk_mul_f32 v[218:219], v[144:145], v[190:191] op_sel_hi:[1,0]
	v_pk_mul_f32 v[232:233], v[142:143], v[192:193] op_sel_hi:[1,0]
	v_pk_mul_f32 v[234:235], v[144:145], v[192:193] op_sel_hi:[1,0]
	v_pk_fma_f32 v[216:217], v[84:85], v[48:49], v[216:217]
	v_pk_fma_f32 v[218:219], v[88:89], v[50:51], v[218:219]
	v_pk_fma_f32 v[232:233], v[100:101], v[48:49], v[232:233]
	v_pk_fma_f32 v[234:235], v[104:105], v[50:51], v[234:235]
	v_pk_fma_f32 v[84:85], v[172:173], v[188:189], v[216:217] op_sel_hi:[1,0,1]
	v_pk_fma_f32 v[88:89], v[174:175], v[188:189], v[218:219] op_sel_hi:[1,0,1]
	v_pk_fma_f32 v[100:101], v[172:173], v[188:189], v[232:233] op_sel:[0,1,0]
	v_pk_fma_f32 v[104:105], v[174:175], v[188:189], v[234:235] op_sel:[0,1,0]
	ds_read_b128 v[142:145], v171 offset:8704
	ds_read_b128 v[48:51], v171 offset:512
	ds_read_b128 v[172:175], v171 offset:4608
	v_pk_mul_f32 v[220:221], v[146:147], v[190:191] op_sel_hi:[1,0]
	v_pk_mul_f32 v[222:223], v[148:149], v[190:191] op_sel_hi:[1,0]
	v_pk_mul_f32 v[236:237], v[146:147], v[192:193] op_sel_hi:[1,0]
	v_pk_mul_f32 v[238:239], v[148:149], v[192:193] op_sel_hi:[1,0]
	v_pk_fma_f32 v[220:221], v[86:87], v[52:53], v[220:221]
	v_pk_fma_f32 v[222:223], v[92:93], v[54:55], v[222:223]
	v_pk_fma_f32 v[236:237], v[106:107], v[52:53], v[236:237]
	v_pk_fma_f32 v[238:239], v[108:109], v[54:55], v[238:239]
	v_pk_fma_f32 v[86:87], v[176:177], v[188:189], v[220:221] op_sel_hi:[1,0,1]
	v_pk_fma_f32 v[92:93], v[178:179], v[188:189], v[222:223] op_sel_hi:[1,0,1]
	v_pk_fma_f32 v[106:107], v[176:177], v[188:189], v[236:237] op_sel:[0,1,0]
	v_pk_fma_f32 v[108:109], v[178:179], v[188:189], v[238:239] op_sel:[0,1,0]
	ds_read_b128 v[146:149], v171 offset:8720
	ds_read_b128 v[52:55], v171 offset:528
	ds_read_b128 v[176:179], v171 offset:4624
	v_pk_mul_f32 v[224:225], v[150:151], v[190:191] op_sel_hi:[1,0]
	v_pk_mul_f32 v[226:227], v[152:153], v[190:191] op_sel_hi:[1,0]
	v_pk_mul_f32 v[240:241], v[150:151], v[192:193] op_sel_hi:[1,0]
	v_pk_mul_f32 v[242:243], v[152:153], v[192:193] op_sel_hi:[1,0]
	v_pk_fma_f32 v[224:225], v[90:91], v[56:57], v[224:225]
	v_pk_fma_f32 v[226:227], v[98:99], v[58:59], v[226:227]
	v_pk_fma_f32 v[240:241], v[110:111], v[56:57], v[240:241]
	v_pk_fma_f32 v[242:243], v[112:113], v[58:59], v[242:243]
	v_pk_fma_f32 v[90:91], v[180:181], v[188:189], v[224:225] op_sel_hi:[1,0,1]
	v_pk_fma_f32 v[98:99], v[182:183], v[188:189], v[226:227] op_sel_hi:[1,0,1]
	v_pk_fma_f32 v[110:111], v[180:181], v[188:189], v[240:241] op_sel:[0,1,0]
	v_pk_fma_f32 v[112:113], v[182:183], v[188:189], v[242:243] op_sel:[0,1,0]
	ds_read_b128 v[150:153], v171 offset:8736
	ds_read_b128 v[56:59], v171 offset:544
	ds_read_b128 v[180:183], v171 offset:4640
	v_pk_mul_f32 v[228:229], v[154:155], v[190:191] op_sel_hi:[1,0]
	v_pk_mul_f32 v[230:231], v[156:157], v[190:191] op_sel_hi:[1,0]
	v_pk_mul_f32 v[244:245], v[154:155], v[192:193] op_sel_hi:[1,0]
	v_pk_mul_f32 v[246:247], v[156:157], v[192:193] op_sel_hi:[1,0]
	v_pk_fma_f32 v[228:229], v[94:95], v[60:61], v[228:229]
	v_pk_fma_f32 v[230:231], v[102:103], v[62:63], v[230:231]
	v_pk_fma_f32 v[244:245], v[114:115], v[60:61], v[244:245]
	v_pk_fma_f32 v[246:247], v[116:117], v[62:63], v[246:247]
	v_pk_fma_f32 v[94:95], v[184:185], v[188:189], v[228:229] op_sel_hi:[1,0,1]
	v_pk_fma_f32 v[102:103], v[186:187], v[188:189], v[230:231] op_sel_hi:[1,0,1]
	v_pk_fma_f32 v[114:115], v[184:185], v[188:189], v[244:245] op_sel:[0,1,0]
	v_pk_fma_f32 v[116:117], v[186:187], v[188:189], v[246:247] op_sel:[0,1,0]
	ds_read_b128 v[154:157], v171 offset:8752
	ds_read_b128 v[60:63], v171 offset:560
	ds_read_b128 v[184:187], v171 offset:4656
	ds_read_b64 v[188:189], v96 offset:512
	s_waitcnt lgkmcnt(15)
	v_pk_fma_f32 v[248:249], v[200:201], v[84:85], 0 op_sel_hi:[1,1,0]
	v_pk_fma_f32 v[250:251], v[202:203], v[88:89], 0 op_sel_hi:[1,1,0]
	v_pk_fma_f32 v[194:195], v[200:201], v[100:101], 0 op_sel_hi:[1,1,0]
	v_pk_fma_f32 v[158:159], v[202:203], v[104:105], 0 op_sel_hi:[1,1,0]
	v_pk_fma_f32 v[248:249], v[204:205], v[86:87], v[248:249]
	v_pk_fma_f32 v[250:251], v[206:207], v[92:93], v[250:251]
	v_pk_fma_f32 v[194:195], v[204:205], v[106:107], v[194:195]
	v_pk_fma_f32 v[158:159], v[206:207], v[108:109], v[158:159]
	v_pk_fma_f32 v[248:249], v[208:209], v[90:91], v[248:249]
	v_pk_fma_f32 v[250:251], v[210:211], v[98:99], v[250:251]
	v_pk_fma_f32 v[194:195], v[208:209], v[110:111], v[194:195]
	v_pk_fma_f32 v[158:159], v[210:211], v[112:113], v[158:159]
	v_pk_fma_f32 v[248:249], v[212:213], v[94:95], v[248:249]
	v_pk_fma_f32 v[250:251], v[214:215], v[102:103], v[250:251]
	v_pk_fma_f32 v[194:195], v[212:213], v[114:115], v[194:195]
	v_pk_fma_f32 v[158:159], v[214:215], v[116:117], v[158:159]
	v_pk_add_f32 v[248:249], v[250:251], v[248:249]
	v_pk_add_f32 v[194:195], v[158:159], v[194:195]
	ds_read_b128 v[200:203], v171 offset:16896
	v_add_f32_e32 v168, v248, v249
	v_add_f32_e32 v169, v194, v195
	ds_read_b128 v[204:207], v171 offset:16912
	v_add_f32_dpp v168, v168, v168 quad_perm:[1,0,3,2] row_mask:0xf bank_mask:0xf bound_ctrl:1
	v_add_f32_dpp v169, v169, v169 quad_perm:[1,0,3,2] row_mask:0xf bank_mask:0xf bound_ctrl:1
	ds_read_b128 v[208:211], v171 offset:16928
	v_add_f32_dpp v168, v168, v168 quad_perm:[2,3,0,1] row_mask:0xf bank_mask:0xf bound_ctrl:1
	v_add_f32_dpp v169, v169, v169 quad_perm:[2,3,0,1] row_mask:0xf bank_mask:0xf bound_ctrl:1
	ds_read_b128 v[212:215], v171 offset:16944
	s_and_saveexec_b64 s[34:35], s[8:9]
	ds_write_b64 v75, v[168:169] offset:256
	s_or_b64 exec, exec, s[34:35]
	v_add_u32_e32 v171, 0x200, v171
	v_add_u32_e32 v96, 0x200, v96
	v_add_u32_e32 v75, 0x200, v75
	s_addk_i32 s82, 0x200
	s_cmpk_eq_i32 s82, 0x1000
	s_cbranch_scc0 .Lscan_step
	s_branch .LBB0_162
